# MLA loop: VALU (max/exp/cvt) redistributed under the MFMA groups (1-3 VALU per MFMA), V fragments requested earlier, PV of half 1 in query-block-major order; plus all earlier edits
# speedup vs baseline: 1.0104x; 1.0104x over previous
; template <int DQK, bool MASK, int NQ>
; __device__ __forceinline__ void attn_unit(unsigned char* lds, const bf16_t* Qg, int ldq, const bf16_t* Kg, int ldk, const bf16_t* Vtg, bf16_t* Og, int ldo,
;                                           int qi0, int a0, int n1, int b0, int n2, float m0, bool sink) {
;     ...
;             { const unsigned char* kb_ = lds + KOFF + (tt & 1) * KBYTES + hb * 512 + g * 1024 + ql * 16;
;               __builtin_amdgcn_s_setprio(1);
; #pragma unroll
;               for (int k2 = 0; k2 < 2; ++k2) {
; #pragma unroll
;                   for (int c = 0; c < NC; ++c) {
;                       const bf16x8 kf = *(const bf16x8*)(kb_ + c * 4096 + k2 * 256);
; #pragma unroll
;                       for (int qb = 0; qb < NQ; ++qb) sc[k2][qb] = __builtin_amdgcn_mfma_f32_16x16x32_bf16(kf, qf[qb][c], c == 0 ? negm[qb] : sc[k2][qb], 0, 0, 0);
;                   } }
;               __builtin_amdgcn_s_setprio(0); }
;             if (MASK) { if (kt >= 4) { int dl = kt * 64 + hb * 32 + g * 4 - qw0 - ql; asm volatile("" : "+v"(dl));
; #pragma unroll
;                 for (int k2 = 0; k2 < 2; ++k2)
; #pragma unroll
;                     for (int qb = 0; qb < NQ; ++qb)
; #pragma unroll
;                         for (int j = 0; j < 4; ++j) { const int d = dl + (k2 * 16 + j - qb * 16); if (d > 128 || d < -128) sc[k2][qb][j] = -1e30f; } } }
;             float am = fmaxf(fmaxf(sc[0][0][0], sc[0][0][1]), sc[0][0][2]); am = fmaxf(fmaxf(am, sc[0][0][3]), sc[1][0][0]); am = fmaxf(fmaxf(am, sc[1][0][1]), sc[1][0][2]); am = fmaxf(am, sc[1][0][3]);
; #pragma unroll
;             for (int qb = 1; qb < NQ; ++qb) { am = fmaxf(fmaxf(am, sc[0][qb][0]), sc[0][qb][1]); am = fmaxf(fmaxf(am, sc[0][qb][2]), sc[0][qb][3]);
;                 am = fmaxf(fmaxf(am, sc[1][qb][0]), sc[1][qb][1]); am = fmaxf(fmaxf(am, sc[1][qb][2]), sc[1][qb][3]); }
;             if (__any(first || (am > ATT_THR))) {
; #pragma unroll
;                 for (int qb = 0; qb < NQ; ++qb) {
;                     float a = fmaxf(fmaxf(sc[0][qb][0], sc[0][qb][1]), sc[0][qb][2]);
;                     a = fmaxf(fmaxf(a, sc[0][qb][3]), sc[1][qb][0]); a = fmaxf(fmaxf(a, sc[1][qb][1]), sc[1][qb][2]); a = fmaxf(a, sc[1][qb][3]);
;                     { auto r16 = __builtin_amdgcn_permlane16_swap(__float_as_uint(a), __float_as_uint(a), false, false); a = fmaxf(__uint_as_float(r16[0]), __uint_as_float(r16[1])); }
.Lmla_noload:
	s_and_b32 s0, s13, 1
	s_mul_i32 s1, s0, 0x3000
	s_mulk_i32 s0, 0x2400
	v_add_u32_e32 v37, s1, v250
	v_add_u32_e32 v38, s0, v251
	ds_read_b128 v[196:199], v37
	ds_read_b128 v[192:195], v37 offset:4096
	ds_read_b128 v[188:191], v37 offset:8192
	ds_read_b128 v[184:187], v37 offset:256
	ds_read_b128 v[242:245], v37 offset:4352
	ds_read_b128 v[246:249], v37 offset:8448
	s_waitcnt lgkmcnt(5)
	v_mfma_f32_16x16x32_bf16 v[180:183], v[196:199], v[92:95], v[160:163]
	v_mfma_f32_16x16x32_bf16 v[176:179], v[196:199], v[104:107], v[156:159]
	v_mfma_f32_16x16x32_bf16 v[172:175], v[196:199], v[116:119], v[152:155]
	v_mfma_f32_16x16x32_bf16 v[168:171], v[196:199], v[128:131], v[164:167]
	s_waitcnt lgkmcnt(4)
	v_mfma_f32_16x16x32_bf16 v[180:183], v[192:195], v[96:99], v[180:183]
	v_mfma_f32_16x16x32_bf16 v[176:179], v[192:195], v[108:111], v[176:179]
	v_mfma_f32_16x16x32_bf16 v[172:175], v[192:195], v[120:123], v[172:175]
	v_mfma_f32_16x16x32_bf16 v[168:171], v[192:195], v[132:135], v[168:171]
	s_waitcnt lgkmcnt(3)
	v_mfma_f32_16x16x32_bf16 v[180:183], v[188:191], v[100:103], v[180:183]
	v_mfma_f32_16x16x32_bf16 v[176:179], v[188:191], v[112:115], v[176:179]
	v_mfma_f32_16x16x32_bf16 v[172:175], v[188:191], v[124:127], v[172:175]
	v_mfma_f32_16x16x32_bf16 v[168:171], v[188:191], v[136:139], v[168:171]
	s_waitcnt lgkmcnt(2)
	v_mfma_f32_16x16x32_bf16 v[196:199], v[184:187], v[92:95], v[160:163]
	v_mfma_f32_16x16x32_bf16 v[192:195], v[184:187], v[104:107], v[156:159]
	v_mfma_f32_16x16x32_bf16 v[188:191], v[184:187], v[116:119], v[152:155]
	v_mfma_f32_16x16x32_bf16 v[184:187], v[184:187], v[128:131], v[164:167]
	s_waitcnt lgkmcnt(1)
	v_mfma_f32_16x16x32_bf16 v[196:199], v[242:245], v[96:99], v[196:199]
	v_mfma_f32_16x16x32_bf16 v[192:195], v[242:245], v[108:111], v[192:195]
	v_max_f32_e32 v216, v180, v181
	v_mfma_f32_16x16x32_bf16 v[188:191], v[242:245], v[120:123], v[188:191]
	v_max_f32_e32 v217, v176, v177
	v_mfma_f32_16x16x32_bf16 v[184:187], v[242:245], v[132:135], v[184:187]
	v_max_f32_e32 v218, v172, v173
	s_waitcnt lgkmcnt(0)
	v_mfma_f32_16x16x32_bf16 v[196:199], v[246:249], v[100:103], v[196:199]
	v_max_f32_e32 v219, v168, v169
	v_mfma_f32_16x16x32_bf16 v[192:195], v[246:249], v[112:115], v[192:195]
	v_max3_f32 v216, v216, v182, v183
	v_mfma_f32_16x16x32_bf16 v[188:191], v[246:249], v[124:127], v[188:191]
	v_max3_f32 v217, v217, v178, v179
	v_mfma_f32_16x16x32_bf16 v[184:187], v[246:249], v[136:139], v[184:187]
	v_max3_f32 v218, v218, v174, v175
	ds_read_b128 v[232:235], v37 offset:512
	ds_read_b128 v[44:47], v37 offset:4608
	ds_read_b128 v[200:203], v37 offset:8704
	ds_read_b128 v[236:239], v37 offset:768
	ds_read_b128 v[242:245], v37 offset:4864
	ds_read_b128 v[246:249], v37 offset:8960
	v_max3_f32 v219, v219, v170, v171
	v_max3_f32 v216, v216, v196, v197
	v_max3_f32 v217, v217, v192, v193
	v_max3_f32 v218, v218, v188, v189
	v_max3_f32 v219, v219, v184, v185
	v_max3_f32 v216, v216, v198, v199
	v_max3_f32 v217, v217, v194, v195
	v_max3_f32 v218, v218, v190, v191
	v_max3_f32 v219, v219, v186, v187
	v_max3_f32 v220, v216, v217, v218
	v_max_f32_e32 v220, v220, v219
	v_cmp_lt_f32_e32 vcc, 4.0, v220
	s_or_b64 s[0:1], s[10:11], vcc
	s_cmp_lg_u64 s[0:1], 0
	s_cbranch_scc1 .Lmla_rare_a
.Lmla_common_a:
	s_waitcnt lgkmcnt(5)
	v_mfma_f32_16x16x32_bf16 v[216:219], v[232:235], v[92:95], v[160:163]
	v_exp_f32_e32 v180, v180
	v_exp_f32_e32 v181, v181
	v_exp_f32_e32 v182, v182
	v_mfma_f32_16x16x32_bf16 v[220:223], v[232:235], v[104:107], v[156:159]
	v_exp_f32_e32 v183, v183
	v_exp_f32_e32 v196, v196
	v_exp_f32_e32 v197, v197
	v_mfma_f32_16x16x32_bf16 v[224:227], v[232:235], v[116:119], v[152:155]
	v_exp_f32_e32 v198, v198
	v_exp_f32_e32 v199, v199
	v_cvt_pk_bf16_f32 v180, v180, v181
	v_mfma_f32_16x16x32_bf16 v[228:231], v[232:235], v[128:131], v[164:167]
	v_cvt_pk_bf16_f32 v181, v182, v183
	v_cvt_pk_bf16_f32 v182, v196, v197
	v_cvt_pk_bf16_f32 v183, v198, v199
	s_waitcnt lgkmcnt(4)
	v_mfma_f32_16x16x32_bf16 v[216:219], v[44:47], v[96:99], v[216:219]
	v_exp_f32_e32 v176, v176
	v_exp_f32_e32 v177, v177
	v_exp_f32_e32 v178, v178
	v_mfma_f32_16x16x32_bf16 v[220:223], v[44:47], v[108:111], v[220:223]
	v_exp_f32_e32 v179, v179
	v_exp_f32_e32 v192, v192
	v_exp_f32_e32 v193, v193
	v_mfma_f32_16x16x32_bf16 v[224:227], v[44:47], v[120:123], v[224:227]
	v_exp_f32_e32 v194, v194
	v_exp_f32_e32 v195, v195
	v_cvt_pk_bf16_f32 v176, v176, v177
	v_mfma_f32_16x16x32_bf16 v[228:231], v[44:47], v[132:135], v[228:231]
	v_cvt_pk_bf16_f32 v177, v178, v179
	v_cvt_pk_bf16_f32 v178, v192, v193
	v_cvt_pk_bf16_f32 v179, v194, v195
	s_waitcnt lgkmcnt(3)
	v_mfma_f32_16x16x32_bf16 v[216:219], v[200:203], v[100:103], v[216:219]
	v_exp_f32_e32 v172, v172
	v_exp_f32_e32 v173, v173
	v_exp_f32_e32 v174, v174
	v_mfma_f32_16x16x32_bf16 v[220:223], v[200:203], v[112:115], v[220:223]
	v_exp_f32_e32 v175, v175
	v_exp_f32_e32 v188, v188
	v_exp_f32_e32 v189, v189
	v_mfma_f32_16x16x32_bf16 v[224:227], v[200:203], v[124:127], v[224:227]
	v_exp_f32_e32 v190, v190
	v_exp_f32_e32 v191, v191
	v_cvt_pk_bf16_f32 v172, v172, v173
	v_mfma_f32_16x16x32_bf16 v[228:231], v[200:203], v[136:139], v[228:231]
	v_cvt_pk_bf16_f32 v173, v174, v175
	v_cvt_pk_bf16_f32 v174, v188, v189
	v_cvt_pk_bf16_f32 v175, v190, v191
	s_waitcnt lgkmcnt(2)
; template <int DQK, bool MASK, int NQ>
; __device__ __forceinline__ void attn_unit(unsigned char* lds, const bf16_t* Qg, int ldq, const bf16_t* Kg, int ldk, const bf16_t* Vtg, bf16_t* Og, int ldo,
;                                           int qi0, int a0, int n1, int b0, int n2, float m0, bool sink) {
;     ...
;             float am = fmaxf(fmaxf(sc[0][0][0], sc[0][0][1]), sc[0][0][2]); am = fmaxf(fmaxf(am, sc[0][0][3]), sc[1][0][0]); am = fmaxf(fmaxf(am, sc[1][0][1]), sc[1][0][2]); am = fmaxf(am, sc[1][0][3]);
; #pragma unroll
;             for (int qb = 1; qb < NQ; ++qb) { am = fmaxf(fmaxf(am, sc[0][qb][0]), sc[0][qb][1]); am = fmaxf(fmaxf(am, sc[0][qb][2]), sc[0][qb][3]);
;                 am = fmaxf(fmaxf(am, sc[1][qb][0]), sc[1][qb][1]); am = fmaxf(fmaxf(am, sc[1][qb][2]), sc[1][qb][3]); }
;             if (__any(first || (am > ATT_THR))) {
; #pragma unroll
;                 for (int qb = 0; qb < NQ; ++qb) {
;                     float a = fmaxf(fmaxf(sc[0][qb][0], sc[0][qb][1]), sc[0][qb][2]);
;                     a = fmaxf(fmaxf(a, sc[0][qb][3]), sc[1][qb][0]); a = fmaxf(fmaxf(a, sc[1][qb][1]), sc[1][qb][2]); a = fmaxf(a, sc[1][qb][3]);
;                     { auto r16 = __builtin_amdgcn_permlane16_swap(__float_as_uint(a), __float_as_uint(a), false, false); a = fmaxf(__uint_as_float(r16[0]), __uint_as_float(r16[1])); }
;                     { auto r32 = __builtin_amdgcn_permlane32_swap(__float_as_uint(a), __float_as_uint(a), false, false); a = fmaxf(__uint_as_float(r32[0]), __uint_as_float(r32[1])); }
;                     const float dlt = first ? a : fmaxf(a, 0.f);
;                     mrow[qb] += dlt; negm[qb] = (f32x4){-mrow[qb], -mrow[qb], -mrow[qb], -mrow[qb]};
;                     sc[0][qb] = sc[0][qb] - dlt; sc[1][qb] = sc[1][qb] - dlt;
;                     if (!first) { const float alpha = __builtin_amdgcn_exp2f(-dlt); ol[qb] = ol[qb] * alpha;
; #pragma unroll
;                         for (int eb = 0; eb < 4; ++eb) o[eb][qb] = o[eb][qb] * alpha; } }
;                 first = false; }
;             bf16x8 pf[NQ];
; #pragma unroll
;             for (int qb = 0; qb < NQ; ++qb) {
; #pragma unroll
;                 for (int k2 = 0; k2 < 2; ++k2)
; #pragma unroll
;                     for (int j = 0; j < 4; ++j) sc[k2][qb][j] = __builtin_amdgcn_exp2f(sc[k2][qb][j]);
	v_mfma_f32_16x16x32_bf16 v[232:235], v[236:239], v[92:95], v[160:163]
	v_exp_f32_e32 v168, v168
	v_exp_f32_e32 v169, v169
	v_exp_f32_e32 v170, v170
	v_mfma_f32_16x16x32_bf16 v[44:47], v[236:239], v[104:107], v[156:159]
	v_exp_f32_e32 v171, v171
	v_exp_f32_e32 v184, v184
	v_exp_f32_e32 v185, v185
	v_mfma_f32_16x16x32_bf16 v[200:203], v[236:239], v[116:119], v[152:155]
	v_exp_f32_e32 v186, v186
	v_exp_f32_e32 v187, v187
	v_cvt_pk_bf16_f32 v168, v168, v169
	v_mfma_f32_16x16x32_bf16 v[236:239], v[236:239], v[128:131], v[164:167]
	v_cvt_pk_bf16_f32 v169, v170, v171
	v_cvt_pk_bf16_f32 v170, v184, v185
	v_cvt_pk_bf16_f32 v171, v186, v187
	ds_read_b128 v[196:199], v38 offset:24576
	ds_read_b128 v[192:195], v38 offset:26880
	ds_read_b128 v[188:191], v38 offset:29184
	ds_read_b128 v[184:187], v38 offset:31488
	s_waitcnt lgkmcnt(5)
	v_mfma_f32_16x16x32_bf16 v[232:235], v[242:245], v[96:99], v[232:235]
	v_mfma_f32_16x16x32_bf16 v[44:47], v[242:245], v[108:111], v[44:47]
	v_mfma_f32_16x16x32_bf16 v[200:203], v[242:245], v[120:123], v[200:203]
	v_mfma_f32_16x16x32_bf16 v[236:239], v[242:245], v[132:135], v[236:239]
	s_waitcnt lgkmcnt(4)
	v_mfma_f32_16x16x32_bf16 v[232:235], v[246:249], v[100:103], v[232:235]
	v_mfma_f32_16x16x32_bf16 v[44:47], v[246:249], v[112:115], v[44:47]
	v_mfma_f32_16x16x32_bf16 v[200:203], v[246:249], v[124:127], v[200:203]
	v_mfma_f32_16x16x32_bf16 v[236:239], v[246:249], v[136:139], v[236:239]
	v_mov_b32_e32 v246, s12
	v_mov_b32_e32 v247, s12
	v_mov_b32_e32 v248, s12
	v_mov_b32_e32 v249, s12
	s_waitcnt lgkmcnt(3)
	v_mfma_f32_16x16x32_bf16 v[76:79], v[196:199], v[180:183], v[76:79]
	v_max_f32_e32 v242, v216, v217
	v_mfma_f32_16x16x32_bf16 v[56:59], v[196:199], v[176:179], v[56:59]
	v_max_f32_e32 v243, v220, v221
	v_mfma_f32_16x16x32_bf16 v[24:27], v[196:199], v[172:175], v[24:27]
	v_max_f32_e32 v244, v224, v225
	v_mfma_f32_16x16x32_bf16 v[4:7], v[196:199], v[168:171], v[4:7]
	v_max_f32_e32 v245, v228, v229
	s_waitcnt lgkmcnt(2)
	v_mfma_f32_16x16x32_bf16 v[80:83], v[192:195], v[180:183], v[80:83]
	v_max3_f32 v242, v242, v218, v219
	v_mfma_f32_16x16x32_bf16 v[60:63], v[192:195], v[176:179], v[60:63]
	v_max3_f32 v243, v243, v222, v223
	v_mfma_f32_16x16x32_bf16 v[28:31], v[192:195], v[172:175], v[28:31]
	v_max3_f32 v244, v244, v226, v227
	v_mfma_f32_16x16x32_bf16 v[8:11], v[192:195], v[168:171], v[8:11]
	v_max3_f32 v245, v245, v230, v231
	s_waitcnt lgkmcnt(1)
	v_mfma_f32_16x16x32_bf16 v[84:87], v[188:191], v[180:183], v[84:87]
	v_max3_f32 v242, v242, v232, v233
	v_mfma_f32_16x16x32_bf16 v[64:67], v[188:191], v[176:179], v[64:67]
	v_max3_f32 v243, v243, v44, v45
	v_mfma_f32_16x16x32_bf16 v[32:35], v[188:191], v[172:175], v[32:35]
	v_max3_f32 v244, v244, v200, v201
	v_mfma_f32_16x16x32_bf16 v[12:15], v[188:191], v[168:171], v[12:15]
	v_max3_f32 v245, v245, v236, v237
	s_waitcnt lgkmcnt(0)
	v_mfma_f32_16x16x32_bf16 v[72:75], v[184:187], v[180:183], v[72:75]
	v_max3_f32 v242, v242, v234, v235
	v_mfma_f32_16x16x32_bf16 v[52:55], v[184:187], v[176:179], v[52:55]
	v_max3_f32 v243, v243, v46, v47
	v_mfma_f32_16x16x32_bf16 v[20:23], v[184:187], v[172:175], v[20:23]
	v_max3_f32 v244, v244, v202, v203
	v_mfma_f32_16x16x32_bf16 v[0:3], v[184:187], v[168:171], v[0:3]
	v_max3_f32 v245, v245, v238, v239
	v_mfma_f32_16x16x32_bf16 v[88:91], v[246:249], v[180:183], v[88:91]
	v_max3_f32 v39, v242, v243, v244
	v_mfma_f32_16x16x32_bf16 v[68:71], v[246:249], v[176:179], v[68:71]
	v_max_f32_e32 v39, v39, v245
	v_mfma_f32_16x16x32_bf16 v[48:51], v[246:249], v[172:175], v[48:51]
	v_mfma_f32_16x16x32_bf16 v[16:19], v[246:249], v[168:171], v[16:19]
	v_cmp_lt_f32_e32 vcc, 4.0, v39
	s_or_b64 s[0:1], s[10:11], vcc
	s_cmp_lg_u64 s[0:1], 0
	s_cbranch_scc1 .Lmla_rare_b
; __device__ __forceinline__ unsigned pk2(float lo, float hi) { f32x2_t v = {lo, hi}; bf16x2_t b = __builtin_convertvector(v, bf16x2_t); return __builtin_bit_cast(unsigned, b); }
; template <int DQK, bool MASK, int NQ>
; __device__ __forceinline__ void attn_unit(unsigned char* lds, const bf16_t* Qg, int ldq, const bf16_t* Kg, int ldk, const bf16_t* Vtg, bf16_t* Og, int ldo,
;                                           int qi0, int a0, int n1, int b0, int n2, float m0, bool sink) {
;     ...
;             for (int qb = 0; qb < NQ; ++qb) {
; #pragma unroll
;                 for (int k2 = 0; k2 < 2; ++k2)
; #pragma unroll
;                     for (int j = 0; j < 4; ++j) sc[k2][qb][j] = __builtin_amdgcn_exp2f(sc[k2][qb][j]);
;                 u32x4 w; w.x = pk2(sc[0][qb][0], sc[0][qb][1]); w.y = pk2(sc[0][qb][2], sc[0][qb][3]); w.z = pk2(sc[1][qb][0], sc[1][qb][1]); w.w = pk2(sc[1][qb][2], sc[1][qb][3]);
;                 pf[qb] = __builtin_bit_cast(bf16x8, w); }
;             { const unsigned char* vb_ = lds + VOFF + (tt & 1) * VBYTES + (hb * 4 + g) * 16;
; #pragma unroll
;               for (int eb = 0; eb < 4; ++eb) {
;                   const bf16x8 vf = *(const bf16x8*)(vb_ + (eb * 16 + ql) * (VP * 2));
; #pragma unroll
;                   for (int qb = 0; qb < NQ; ++qb) o[eb][qb] = __builtin_amdgcn_mfma_f32_16x16x32_bf16(vf, pf[qb], o[eb][qb], 0, 0, 0);
;               }
; #pragma unroll
;               for (int qb = 0; qb < NQ; ++qb) ol[qb] = __builtin_amdgcn_mfma_f32_16x16x32_bf16(ones, pf[qb], ol[qb], 0, 0, 0); }
;           }
;         }
;         if (tt + 1 < nt) ATT_COMMIT((tt + 1) & 1);
.Lmla_common_b:
	ds_read_b128 v[196:199], v38 offset:24640
	ds_read_b128 v[192:195], v38 offset:26944
	ds_read_b128 v[188:191], v38 offset:29248
	ds_read_b128 v[184:187], v38 offset:31552
	v_exp_f32_e32 v216, v216
	v_exp_f32_e32 v217, v217
	v_exp_f32_e32 v218, v218
	v_exp_f32_e32 v219, v219
	v_exp_f32_e32 v232, v232
	v_exp_f32_e32 v233, v233
	v_exp_f32_e32 v234, v234
	v_exp_f32_e32 v235, v235
	v_cvt_pk_bf16_f32 v216, v216, v217
	v_cvt_pk_bf16_f32 v217, v218, v219
	v_cvt_pk_bf16_f32 v218, v232, v233
	v_cvt_pk_bf16_f32 v219, v234, v235
	s_nop 1
	s_waitcnt lgkmcnt(3)
	v_mfma_f32_16x16x32_bf16 v[76:79], v[196:199], v[216:219], v[76:79]
	v_exp_f32_e32 v220, v220
	v_exp_f32_e32 v221, v221
	v_exp_f32_e32 v222, v222
	s_waitcnt lgkmcnt(2)
	v_mfma_f32_16x16x32_bf16 v[80:83], v[192:195], v[216:219], v[80:83]
	v_exp_f32_e32 v223, v223
	v_exp_f32_e32 v44, v44
	v_exp_f32_e32 v45, v45
	s_waitcnt lgkmcnt(1)
	v_mfma_f32_16x16x32_bf16 v[84:87], v[188:191], v[216:219], v[84:87]
	v_exp_f32_e32 v46, v46
	v_exp_f32_e32 v47, v47
	v_cvt_pk_bf16_f32 v220, v220, v221
	s_waitcnt lgkmcnt(0)
	v_mfma_f32_16x16x32_bf16 v[72:75], v[184:187], v[216:219], v[72:75]
	v_cvt_pk_bf16_f32 v221, v222, v223
	v_cvt_pk_bf16_f32 v222, v44, v45
	v_cvt_pk_bf16_f32 v223, v46, v47
	v_mfma_f32_16x16x32_bf16 v[88:91], v[246:249], v[216:219], v[88:91]
	v_mfma_f32_16x16x32_bf16 v[56:59], v[196:199], v[220:223], v[56:59]
	v_exp_f32_e32 v224, v224
	v_exp_f32_e32 v225, v225
	v_exp_f32_e32 v226, v226
	v_mfma_f32_16x16x32_bf16 v[60:63], v[192:195], v[220:223], v[60:63]
	v_exp_f32_e32 v227, v227
	v_exp_f32_e32 v200, v200
	v_exp_f32_e32 v201, v201
	v_mfma_f32_16x16x32_bf16 v[64:67], v[188:191], v[220:223], v[64:67]
	v_exp_f32_e32 v202, v202
	v_exp_f32_e32 v203, v203
	v_cvt_pk_bf16_f32 v224, v224, v225
	v_mfma_f32_16x16x32_bf16 v[52:55], v[184:187], v[220:223], v[52:55]
	v_cvt_pk_bf16_f32 v225, v226, v227
	v_cvt_pk_bf16_f32 v226, v200, v201
	v_cvt_pk_bf16_f32 v227, v202, v203
	v_mfma_f32_16x16x32_bf16 v[68:71], v[246:249], v[220:223], v[68:71]
	v_mfma_f32_16x16x32_bf16 v[24:27], v[196:199], v[224:227], v[24:27]
	v_exp_f32_e32 v228, v228
	v_exp_f32_e32 v229, v229
	v_exp_f32_e32 v230, v230
	v_mfma_f32_16x16x32_bf16 v[28:31], v[192:195], v[224:227], v[28:31]
	v_exp_f32_e32 v231, v231
	v_exp_f32_e32 v236, v236
	v_exp_f32_e32 v237, v237
	v_mfma_f32_16x16x32_bf16 v[32:35], v[188:191], v[224:227], v[32:35]
	v_exp_f32_e32 v238, v238
	v_exp_f32_e32 v239, v239
	v_cvt_pk_bf16_f32 v228, v228, v229
	v_mfma_f32_16x16x32_bf16 v[20:23], v[184:187], v[224:227], v[20:23]
	v_cvt_pk_bf16_f32 v229, v230, v231
	v_cvt_pk_bf16_f32 v230, v236, v237
	v_cvt_pk_bf16_f32 v231, v238, v239
	v_mfma_f32_16x16x32_bf16 v[48:51], v[246:249], v[224:227], v[48:51]
	v_mfma_f32_16x16x32_bf16 v[4:7], v[196:199], v[228:231], v[4:7]
	v_mfma_f32_16x16x32_bf16 v[8:11], v[192:195], v[228:231], v[8:11]
	v_mfma_f32_16x16x32_bf16 v[12:15], v[188:191], v[228:231], v[12:15]
	v_mfma_f32_16x16x32_bf16 v[0:3], v[184:187], v[228:231], v[0:3]
	v_mfma_f32_16x16x32_bf16 v[16:19], v[246:249], v[228:231], v[16:19]
	s_cmp_ge_i32 s24, s19
	s_cbranch_scc1 .Lmla_nocommit
	s_and_b32 s0, s24, 1
	s_mul_i32 s1, s0, 0x3000
	v_add_u32_e32 v37, s1, v205
	s_waitcnt vmcnt(1)
	ds_write_b128 v37, v[140:143]
	s_and_saveexec_b64 s[14:15], s[38:39]
	ds_write_b128 v37, v[144:147] offset:8192
	s_or_b64 exec, exec, s[14:15]
	s_mulk_i32 s0, 0x2400
	v_add_u32_e32 v37, s0, v209
	v_add_u32_e32 v37, 0x6000, v37
	s_waitcnt vmcnt(0)
	ds_write2_b64 v37, v[148:149], v[150:151] offset1:2
